# P7 main-path epilogue rewritten like P9: batched residual loads, batched bpermutes, counted waits
# speedup vs baseline: 1.0129x; 1.0045x over previous
; __device__ __forceinline__ unsigned cvt_pk_bf16(float lo, float hi) { unsigned r; asm volatile("v_cvt_pk_bf16_f32 %0, %1, %2" : "=v"(r) : "v"(lo), "v"(hi)); return r; }
;     __device__ __forceinline__ void operator()(const f32x4 (&acc)[2][2][4][2], const pg8::Unit& u, int wr, int wc, int fr, int fq) const {
;     ...
;             for (int m = 0; m < 4; ++m) { const int row = row0 + ai * 128 + m * 16;
;                 if (row < MV) {
;                     const float* rp = (row < MPR) ? res_p + (size_t)row * DM : res_s + (size_t)(row - MPR) * DM;
;                     float s = 0.f;
; #pragma unroll
;                     for (int bj = 0; bj < 2; ++bj)
; #pragma unroll
;                         for (int n = 0; n < 2; ++n) { const int col = col0 + bj * 128 + n * 16; f32x4 r;
;                             if (RESB) { const u32x2 rw = *(const u32x2*)(resb + (size_t)row * DM + col); r = (f32x4){bf2f(rw.x & 0xffff), bf2f(rw.x >> 16), bf2f(rw.y & 0xffff), bf2f(rw.y >> 16)}; }
;                             else r = *(const f32x4*)(rp + col);
;                             const f32x4 v = r + acc[ai][bj][m][n] * scale;
;                             if (OUTF) *(f32x4*)(out + (size_t)row * DM + col) = v;
;                             else { u32x2 w; w.x = cvt_pk_bf16(v[0], v[1]); w.y = cvt_pk_bf16(v[2], v[3]); *(u32x2*)(outb + (size_t)row * DM + col) = w;
;                                 s += (v[0] * v[0] + v[1] * v[1]) + (v[2] * v[2] + v[3] * v[3]); } }
.LBB0_1056:
	s_cmp_lt_i32 s76, 2
	s_cbranch_scc0 .LBB0_1086
	v_lshl_add_u32 v160, s46, 8, v164
	v_lshl_or_b32 v161, s44, 8, v166
	v_lshlrev_b32_e32 v160, 11, v160
	v_lshl_add_u32 v160, v161, 1, v160
	global_load_dwordx2 v[176:177], v160, s[16:17]
	global_load_dwordx2 v[178:179], v160, s[16:17] offset:32
	global_load_dwordx2 v[180:181], v160, s[16:17] offset:256
	global_load_dwordx2 v[182:183], v160, s[16:17] offset:288
	v_add_u32_e32 v161, 0x8000, v160
	global_load_dwordx2 v[184:185], v161, s[16:17]
	global_load_dwordx2 v[186:187], v161, s[16:17] offset:32
	global_load_dwordx2 v[188:189], v161, s[16:17] offset:256
	global_load_dwordx2 v[190:191], v161, s[16:17] offset:288
	v_add_u32_e32 v161, 0x10000, v160
	global_load_dwordx2 v[192:193], v161, s[16:17]
	global_load_dwordx2 v[194:195], v161, s[16:17] offset:32
	global_load_dwordx2 v[196:197], v161, s[16:17] offset:256
	global_load_dwordx2 v[198:199], v161, s[16:17] offset:288
	v_add_u32_e32 v161, 0x18000, v160
	global_load_dwordx2 v[200:201], v161, s[16:17]
	global_load_dwordx2 v[202:203], v161, s[16:17] offset:32
	global_load_dwordx2 v[204:205], v161, s[16:17] offset:256
	global_load_dwordx2 v[206:207], v161, s[16:17] offset:288
	v_add_u32_e32 v161, 0x40000, v160
	global_load_dwordx2 v[208:209], v161, s[16:17]
	global_load_dwordx2 v[210:211], v161, s[16:17] offset:32
	global_load_dwordx2 v[212:213], v161, s[16:17] offset:256
	global_load_dwordx2 v[214:215], v161, s[16:17] offset:288
	v_add_u32_e32 v161, 0x48000, v160
	global_load_dwordx2 v[144:145], v161, s[16:17]
	global_load_dwordx2 v[146:147], v161, s[16:17] offset:32
	global_load_dwordx2 v[148:149], v161, s[16:17] offset:256
	global_load_dwordx2 v[150:151], v161, s[16:17] offset:288
	v_add_u32_e32 v161, 0x50000, v160
	global_load_dwordx2 v[152:153], v161, s[16:17]
	global_load_dwordx2 v[154:155], v161, s[16:17] offset:32
	global_load_dwordx2 v[156:157], v161, s[16:17] offset:256
	global_load_dwordx2 v[158:159], v161, s[16:17] offset:288
	s_waitcnt vmcnt(24)
	v_and_b32_e32 v162, 0xffff0000, v176
	v_lshlrev_b32_e32 v176, 16, v176
	v_and_b32_e32 v163, 0xffff0000, v177
	v_lshlrev_b32_e32 v177, 16, v177
	v_add_f32_e32 v64, v64, v176
	v_add_f32_e32 v65, v65, v162
	v_add_f32_e32 v66, v66, v177
	v_add_f32_e32 v67, v67, v163
	v_mul_f32_e32 v176, v65, v65
	v_mul_f32_e32 v177, v67, v67
	v_fmac_f32_e32 v176, v64, v64
	v_fmac_f32_e32 v177, v66, v66
	v_add_f32_e32 v176, v176, v177
	v_mov_b32_e32 v172, v176
	v_cvt_pk_bf16_f32 v64, v64, v65
	v_cvt_pk_bf16_f32 v65, v66, v67
	v_and_b32_e32 v162, 0xffff0000, v178
	v_lshlrev_b32_e32 v178, 16, v178
	v_and_b32_e32 v163, 0xffff0000, v179
	v_lshlrev_b32_e32 v179, 16, v179
	v_add_f32_e32 v60, v60, v178
	v_add_f32_e32 v61, v61, v162
	v_add_f32_e32 v62, v62, v179
	v_add_f32_e32 v63, v63, v163
	v_mul_f32_e32 v178, v61, v61
	v_mul_f32_e32 v179, v63, v63
	v_fmac_f32_e32 v178, v60, v60
	v_fmac_f32_e32 v179, v62, v62
	v_add_f32_e32 v178, v178, v179
	v_add_f32_e32 v172, v172, v178
	v_cvt_pk_bf16_f32 v60, v60, v61
	v_cvt_pk_bf16_f32 v61, v62, v63
	v_and_b32_e32 v162, 0xffff0000, v180
	v_lshlrev_b32_e32 v180, 16, v180
	v_and_b32_e32 v163, 0xffff0000, v181
	v_lshlrev_b32_e32 v181, 16, v181
	v_add_f32_e32 v52, v52, v180
	v_add_f32_e32 v53, v53, v162
	v_add_f32_e32 v54, v54, v181
	v_add_f32_e32 v55, v55, v163
	v_mul_f32_e32 v180, v53, v53
	v_mul_f32_e32 v181, v55, v55
	v_fmac_f32_e32 v180, v52, v52
	v_fmac_f32_e32 v181, v54, v54
	v_add_f32_e32 v180, v180, v181
	v_add_f32_e32 v172, v172, v180
	v_cvt_pk_bf16_f32 v52, v52, v53
	v_cvt_pk_bf16_f32 v53, v54, v55
	v_and_b32_e32 v162, 0xffff0000, v182
	v_lshlrev_b32_e32 v182, 16, v182
	v_and_b32_e32 v163, 0xffff0000, v183
	v_lshlrev_b32_e32 v183, 16, v183
	v_add_f32_e32 v44, v44, v182
	v_add_f32_e32 v45, v45, v162
	v_add_f32_e32 v46, v46, v183
	v_add_f32_e32 v47, v47, v163
	v_mul_f32_e32 v182, v45, v45
	v_mul_f32_e32 v183, v47, v47
	v_fmac_f32_e32 v182, v44, v44
	v_fmac_f32_e32 v183, v46, v46
	v_add_f32_e32 v182, v182, v183
	v_add_f32_e32 v172, v172, v182
	v_cvt_pk_bf16_f32 v44, v44, v45
	v_cvt_pk_bf16_f32 v45, v46, v47
	v_mov_b32_e32 v66, v172
	v_add_u32_e32 v161, 0x58000, v160
	global_load_dwordx2 v[176:177], v161, s[16:17]
	global_load_dwordx2 v[178:179], v161, s[16:17] offset:32
	global_load_dwordx2 v[180:181], v161, s[16:17] offset:256
	global_load_dwordx2 v[182:183], v161, s[16:17] offset:288
	global_store_dwordx2 v160, v[64:65], s[18:19]
	global_store_dwordx2 v160, v[60:61], s[18:19] offset:32
	global_store_dwordx2 v160, v[52:53], s[18:19] offset:256
	global_store_dwordx2 v160, v[44:45], s[18:19] offset:288
	s_waitcnt vmcnt(28)
; __device__ __forceinline__ unsigned cvt_pk_bf16(float lo, float hi) { unsigned r; asm volatile("v_cvt_pk_bf16_f32 %0, %1, %2" : "=v"(r) : "v"(lo), "v"(hi)); return r; }
;     __device__ __forceinline__ void operator()(const f32x4 (&acc)[2][2][4][2], const pg8::Unit& u, int wr, int wc, int fr, int fq) const {
;     ...
;                     for (int bj = 0; bj < 2; ++bj)
; #pragma unroll
;                         for (int n = 0; n < 2; ++n) { const int col = col0 + bj * 128 + n * 16; f32x4 r;
;                             if (RESB) { const u32x2 rw = *(const u32x2*)(resb + (size_t)row * DM + col); r = (f32x4){bf2f(rw.x & 0xffff), bf2f(rw.x >> 16), bf2f(rw.y & 0xffff), bf2f(rw.y >> 16)}; }
;                             else r = *(const f32x4*)(rp + col);
;                             const f32x4 v = r + acc[ai][bj][m][n] * scale;
;                             if (OUTF) *(f32x4*)(out + (size_t)row * DM + col) = v;
;                             else { u32x2 w; w.x = cvt_pk_bf16(v[0], v[1]); w.y = cvt_pk_bf16(v[2], v[3]); *(u32x2*)(outb + (size_t)row * DM + col) = w;
;                                 s += (v[0] * v[0] + v[1] * v[1]) + (v[2] * v[2] + v[3] * v[3]); } }
	v_and_b32_e32 v162, 0xffff0000, v184
	v_lshlrev_b32_e32 v184, 16, v184
	v_and_b32_e32 v163, 0xffff0000, v185
	v_lshlrev_b32_e32 v185, 16, v185
	v_add_f32_e32 v48, v48, v184
	v_add_f32_e32 v49, v49, v162
	v_add_f32_e32 v50, v50, v185
	v_add_f32_e32 v51, v51, v163
	v_mul_f32_e32 v184, v49, v49
	v_mul_f32_e32 v185, v51, v51
	v_fmac_f32_e32 v184, v48, v48
	v_fmac_f32_e32 v185, v50, v50
	v_add_f32_e32 v184, v184, v185
	v_mov_b32_e32 v172, v184
	v_cvt_pk_bf16_f32 v48, v48, v49
	v_cvt_pk_bf16_f32 v49, v50, v51
	v_and_b32_e32 v162, 0xffff0000, v186
	v_lshlrev_b32_e32 v186, 16, v186
	v_and_b32_e32 v163, 0xffff0000, v187
	v_lshlrev_b32_e32 v187, 16, v187
	v_add_f32_e32 v40, v40, v186
	v_add_f32_e32 v41, v41, v162
	v_add_f32_e32 v42, v42, v187
	v_add_f32_e32 v43, v43, v163
	v_mul_f32_e32 v186, v41, v41
	v_mul_f32_e32 v187, v43, v43
	v_fmac_f32_e32 v186, v40, v40
	v_fmac_f32_e32 v187, v42, v42
	v_add_f32_e32 v186, v186, v187
	v_add_f32_e32 v172, v172, v186
	v_cvt_pk_bf16_f32 v40, v40, v41
	v_cvt_pk_bf16_f32 v41, v42, v43
	v_and_b32_e32 v162, 0xffff0000, v188
	v_lshlrev_b32_e32 v188, 16, v188
	v_and_b32_e32 v163, 0xffff0000, v189
	v_lshlrev_b32_e32 v189, 16, v189
	v_add_f32_e32 v36, v36, v188
	v_add_f32_e32 v37, v37, v162
	v_add_f32_e32 v38, v38, v189
	v_add_f32_e32 v39, v39, v163
	v_mul_f32_e32 v188, v37, v37
	v_mul_f32_e32 v189, v39, v39
	v_fmac_f32_e32 v188, v36, v36
	v_fmac_f32_e32 v189, v38, v38
	v_add_f32_e32 v188, v188, v189
	v_add_f32_e32 v172, v172, v188
	v_cvt_pk_bf16_f32 v36, v36, v37
	v_cvt_pk_bf16_f32 v37, v38, v39
	v_and_b32_e32 v162, 0xffff0000, v190
	v_lshlrev_b32_e32 v190, 16, v190
	v_and_b32_e32 v163, 0xffff0000, v191
	v_lshlrev_b32_e32 v191, 16, v191
	v_add_f32_e32 v28, v28, v190
	v_add_f32_e32 v29, v29, v162
	v_add_f32_e32 v30, v30, v191
	v_add_f32_e32 v31, v31, v163
	v_mul_f32_e32 v190, v29, v29
	v_mul_f32_e32 v191, v31, v31
	v_fmac_f32_e32 v190, v28, v28
	v_fmac_f32_e32 v191, v30, v30
	v_add_f32_e32 v190, v190, v191
	v_add_f32_e32 v172, v172, v190
	v_cvt_pk_bf16_f32 v28, v28, v29
	v_cvt_pk_bf16_f32 v29, v30, v31
	v_mov_b32_e32 v50, v172
	v_add_u32_e32 v161, 0x8000, v160
	global_store_dwordx2 v161, v[48:49], s[18:19]
	global_store_dwordx2 v161, v[40:41], s[18:19] offset:32
	global_store_dwordx2 v161, v[36:37], s[18:19] offset:256
	global_store_dwordx2 v161, v[28:29], s[18:19] offset:288
	s_waitcnt vmcnt(28)
	v_and_b32_e32 v162, 0xffff0000, v192
	v_lshlrev_b32_e32 v192, 16, v192
	v_and_b32_e32 v163, 0xffff0000, v193
	v_lshlrev_b32_e32 v193, 16, v193
	v_add_f32_e32 v32, v32, v192
	v_add_f32_e32 v33, v33, v162
	v_add_f32_e32 v34, v34, v193
	v_add_f32_e32 v35, v35, v163
	v_mul_f32_e32 v192, v33, v33
	v_mul_f32_e32 v193, v35, v35
	v_fmac_f32_e32 v192, v32, v32
	v_fmac_f32_e32 v193, v34, v34
	v_add_f32_e32 v192, v192, v193
	v_mov_b32_e32 v172, v192
	v_cvt_pk_bf16_f32 v32, v32, v33
	v_cvt_pk_bf16_f32 v33, v34, v35
	v_and_b32_e32 v162, 0xffff0000, v194
	v_lshlrev_b32_e32 v194, 16, v194
	v_and_b32_e32 v163, 0xffff0000, v195
	v_lshlrev_b32_e32 v195, 16, v195
	v_add_f32_e32 v24, v24, v194
	v_add_f32_e32 v25, v25, v162
	v_add_f32_e32 v26, v26, v195
	v_add_f32_e32 v27, v27, v163
	v_mul_f32_e32 v194, v25, v25
	v_mul_f32_e32 v195, v27, v27
	v_fmac_f32_e32 v194, v24, v24
	v_fmac_f32_e32 v195, v26, v26
	v_add_f32_e32 v194, v194, v195
	v_add_f32_e32 v172, v172, v194
	v_cvt_pk_bf16_f32 v24, v24, v25
	v_cvt_pk_bf16_f32 v25, v26, v27
	v_and_b32_e32 v162, 0xffff0000, v196
	v_lshlrev_b32_e32 v196, 16, v196
	v_and_b32_e32 v163, 0xffff0000, v197
	v_lshlrev_b32_e32 v197, 16, v197
	v_add_f32_e32 v20, v20, v196
	v_add_f32_e32 v21, v21, v162
	v_add_f32_e32 v22, v22, v197
	v_add_f32_e32 v23, v23, v163
	v_mul_f32_e32 v196, v21, v21
	v_mul_f32_e32 v197, v23, v23
	v_fmac_f32_e32 v196, v20, v20
	v_fmac_f32_e32 v197, v22, v22
	v_add_f32_e32 v196, v196, v197
	v_add_f32_e32 v172, v172, v196
	v_cvt_pk_bf16_f32 v20, v20, v21
	v_cvt_pk_bf16_f32 v21, v22, v23
	v_and_b32_e32 v162, 0xffff0000, v198
	v_lshlrev_b32_e32 v198, 16, v198
	v_and_b32_e32 v163, 0xffff0000, v199
	v_lshlrev_b32_e32 v199, 16, v199
	v_add_f32_e32 v12, v12, v198
	v_add_f32_e32 v13, v13, v162
	v_add_f32_e32 v14, v14, v199
	v_add_f32_e32 v15, v15, v163
	v_mul_f32_e32 v198, v13, v13
	v_mul_f32_e32 v199, v15, v15
	v_fmac_f32_e32 v198, v12, v12
	v_fmac_f32_e32 v199, v14, v14
	v_add_f32_e32 v198, v198, v199
	v_add_f32_e32 v172, v172, v198
	v_cvt_pk_bf16_f32 v12, v12, v13
	v_cvt_pk_bf16_f32 v13, v14, v15
	v_mov_b32_e32 v34, v172
	v_add_u32_e32 v161, 0x10000, v160
	global_store_dwordx2 v161, v[32:33], s[18:19]
	global_store_dwordx2 v161, v[24:25], s[18:19] offset:32
	global_store_dwordx2 v161, v[20:21], s[18:19] offset:256
	global_store_dwordx2 v161, v[12:13], s[18:19] offset:288
	s_waitcnt vmcnt(28)
; __device__ __forceinline__ unsigned cvt_pk_bf16(float lo, float hi) { unsigned r; asm volatile("v_cvt_pk_bf16_f32 %0, %1, %2" : "=v"(r) : "v"(lo), "v"(hi)); return r; }
;     __device__ __forceinline__ void operator()(const f32x4 (&acc)[2][2][4][2], const pg8::Unit& u, int wr, int wc, int fr, int fq) const {
;     ...
;                     for (int bj = 0; bj < 2; ++bj)
; #pragma unroll
;                         for (int n = 0; n < 2; ++n) { const int col = col0 + bj * 128 + n * 16; f32x4 r;
;                             if (RESB) { const u32x2 rw = *(const u32x2*)(resb + (size_t)row * DM + col); r = (f32x4){bf2f(rw.x & 0xffff), bf2f(rw.x >> 16), bf2f(rw.y & 0xffff), bf2f(rw.y >> 16)}; }
;                             else r = *(const f32x4*)(rp + col);
;                             const f32x4 v = r + acc[ai][bj][m][n] * scale;
;                             if (OUTF) *(f32x4*)(out + (size_t)row * DM + col) = v;
;                             else { u32x2 w; w.x = cvt_pk_bf16(v[0], v[1]); w.y = cvt_pk_bf16(v[2], v[3]); *(u32x2*)(outb + (size_t)row * DM + col) = w;
;                                 s += (v[0] * v[0] + v[1] * v[1]) + (v[2] * v[2] + v[3] * v[3]); } }
	v_and_b32_e32 v162, 0xffff0000, v200
	v_lshlrev_b32_e32 v200, 16, v200
	v_and_b32_e32 v163, 0xffff0000, v201
	v_lshlrev_b32_e32 v201, 16, v201
	v_add_f32_e32 v16, v16, v200
	v_add_f32_e32 v17, v17, v162
	v_add_f32_e32 v18, v18, v201
	v_add_f32_e32 v19, v19, v163
	v_mul_f32_e32 v200, v17, v17
	v_mul_f32_e32 v201, v19, v19
	v_fmac_f32_e32 v200, v16, v16
	v_fmac_f32_e32 v201, v18, v18
	v_add_f32_e32 v200, v200, v201
	v_mov_b32_e32 v172, v200
	v_cvt_pk_bf16_f32 v16, v16, v17
	v_cvt_pk_bf16_f32 v17, v18, v19
	v_and_b32_e32 v162, 0xffff0000, v202
	v_lshlrev_b32_e32 v202, 16, v202
	v_and_b32_e32 v163, 0xffff0000, v203
	v_lshlrev_b32_e32 v203, 16, v203
	v_add_f32_e32 v8, v8, v202
	v_add_f32_e32 v9, v9, v162
	v_add_f32_e32 v10, v10, v203
	v_add_f32_e32 v11, v11, v163
	v_mul_f32_e32 v202, v9, v9
	v_mul_f32_e32 v203, v11, v11
	v_fmac_f32_e32 v202, v8, v8
	v_fmac_f32_e32 v203, v10, v10
	v_add_f32_e32 v202, v202, v203
	v_add_f32_e32 v172, v172, v202
	v_cvt_pk_bf16_f32 v8, v8, v9
	v_cvt_pk_bf16_f32 v9, v10, v11
	v_and_b32_e32 v162, 0xffff0000, v204
	v_lshlrev_b32_e32 v204, 16, v204
	v_and_b32_e32 v163, 0xffff0000, v205
	v_lshlrev_b32_e32 v205, 16, v205
	v_add_f32_e32 v4, v4, v204
	v_add_f32_e32 v5, v5, v162
	v_add_f32_e32 v6, v6, v205
	v_add_f32_e32 v7, v7, v163
	v_mul_f32_e32 v204, v5, v5
	v_mul_f32_e32 v205, v7, v7
	v_fmac_f32_e32 v204, v4, v4
	v_fmac_f32_e32 v205, v6, v6
	v_add_f32_e32 v204, v204, v205
	v_add_f32_e32 v172, v172, v204
	v_cvt_pk_bf16_f32 v4, v4, v5
	v_cvt_pk_bf16_f32 v5, v6, v7
	v_and_b32_e32 v162, 0xffff0000, v206
	v_lshlrev_b32_e32 v206, 16, v206
	v_and_b32_e32 v163, 0xffff0000, v207
	v_lshlrev_b32_e32 v207, 16, v207
	v_add_f32_e32 v0, v0, v206
	v_add_f32_e32 v1, v1, v162
	v_add_f32_e32 v2, v2, v207
	v_add_f32_e32 v3, v3, v163
	v_mul_f32_e32 v206, v1, v1
	v_mul_f32_e32 v207, v3, v3
	v_fmac_f32_e32 v206, v0, v0
	v_fmac_f32_e32 v207, v2, v2
	v_add_f32_e32 v206, v206, v207
	v_add_f32_e32 v172, v172, v206
	v_cvt_pk_bf16_f32 v0, v0, v1
	v_cvt_pk_bf16_f32 v1, v2, v3
	v_mov_b32_e32 v18, v172
	v_add_u32_e32 v161, 0x18000, v160
	global_store_dwordx2 v161, v[16:17], s[18:19]
	global_store_dwordx2 v161, v[8:9], s[18:19] offset:32
	global_store_dwordx2 v161, v[4:5], s[18:19] offset:256
	global_store_dwordx2 v161, v[0:1], s[18:19] offset:288
	s_waitcnt vmcnt(28)
	v_and_b32_e32 v162, 0xffff0000, v208
	v_lshlrev_b32_e32 v208, 16, v208
	v_and_b32_e32 v163, 0xffff0000, v209
	v_lshlrev_b32_e32 v209, 16, v209
	v_add_f32_e32 v124, v124, v208
	v_add_f32_e32 v125, v125, v162
	v_add_f32_e32 v126, v126, v209
	v_add_f32_e32 v127, v127, v163
	v_mul_f32_e32 v208, v125, v125
	v_mul_f32_e32 v209, v127, v127
	v_fmac_f32_e32 v208, v124, v124
	v_fmac_f32_e32 v209, v126, v126
	v_add_f32_e32 v208, v208, v209
	v_mov_b32_e32 v172, v208
	v_cvt_pk_bf16_f32 v124, v124, v125
	v_cvt_pk_bf16_f32 v125, v126, v127
	v_and_b32_e32 v162, 0xffff0000, v210
	v_lshlrev_b32_e32 v210, 16, v210
	v_and_b32_e32 v163, 0xffff0000, v211
	v_lshlrev_b32_e32 v211, 16, v211
	v_add_f32_e32 v120, v120, v210
	v_add_f32_e32 v121, v121, v162
	v_add_f32_e32 v122, v122, v211
	v_add_f32_e32 v123, v123, v163
	v_mul_f32_e32 v210, v121, v121
	v_mul_f32_e32 v211, v123, v123
	v_fmac_f32_e32 v210, v120, v120
	v_fmac_f32_e32 v211, v122, v122
	v_add_f32_e32 v210, v210, v211
	v_add_f32_e32 v172, v172, v210
	v_cvt_pk_bf16_f32 v120, v120, v121
	v_cvt_pk_bf16_f32 v121, v122, v123
	v_and_b32_e32 v162, 0xffff0000, v212
	v_lshlrev_b32_e32 v212, 16, v212
	v_and_b32_e32 v163, 0xffff0000, v213
	v_lshlrev_b32_e32 v213, 16, v213
	v_add_f32_e32 v116, v116, v212
	v_add_f32_e32 v117, v117, v162
	v_add_f32_e32 v118, v118, v213
	v_add_f32_e32 v119, v119, v163
	v_mul_f32_e32 v212, v117, v117
	v_mul_f32_e32 v213, v119, v119
	v_fmac_f32_e32 v212, v116, v116
	v_fmac_f32_e32 v213, v118, v118
	v_add_f32_e32 v212, v212, v213
	v_add_f32_e32 v172, v172, v212
	v_cvt_pk_bf16_f32 v116, v116, v117
	v_cvt_pk_bf16_f32 v117, v118, v119
	v_and_b32_e32 v162, 0xffff0000, v214
	v_lshlrev_b32_e32 v214, 16, v214
	v_and_b32_e32 v163, 0xffff0000, v215
	v_lshlrev_b32_e32 v215, 16, v215
	v_add_f32_e32 v112, v112, v214
	v_add_f32_e32 v113, v113, v162
	v_add_f32_e32 v114, v114, v215
	v_add_f32_e32 v115, v115, v163
	v_mul_f32_e32 v214, v113, v113
	v_mul_f32_e32 v215, v115, v115
	v_fmac_f32_e32 v214, v112, v112
	v_fmac_f32_e32 v215, v114, v114
	v_add_f32_e32 v214, v214, v215
	v_add_f32_e32 v172, v172, v214
	v_cvt_pk_bf16_f32 v112, v112, v113
	v_cvt_pk_bf16_f32 v113, v114, v115
	v_mov_b32_e32 v126, v172
	v_add_u32_e32 v161, 0x40000, v160
	global_store_dwordx2 v161, v[124:125], s[18:19]
	global_store_dwordx2 v161, v[120:121], s[18:19] offset:32
	global_store_dwordx2 v161, v[116:117], s[18:19] offset:256
	global_store_dwordx2 v161, v[112:113], s[18:19] offset:288
	s_waitcnt vmcnt(28)
; __device__ __forceinline__ unsigned cvt_pk_bf16(float lo, float hi) { unsigned r; asm volatile("v_cvt_pk_bf16_f32 %0, %1, %2" : "=v"(r) : "v"(lo), "v"(hi)); return r; }
;     __device__ __forceinline__ void operator()(const f32x4 (&acc)[2][2][4][2], const pg8::Unit& u, int wr, int wc, int fr, int fq) const {
;     ...
;                     for (int bj = 0; bj < 2; ++bj)
; #pragma unroll
;                         for (int n = 0; n < 2; ++n) { const int col = col0 + bj * 128 + n * 16; f32x4 r;
;                             if (RESB) { const u32x2 rw = *(const u32x2*)(resb + (size_t)row * DM + col); r = (f32x4){bf2f(rw.x & 0xffff), bf2f(rw.x >> 16), bf2f(rw.y & 0xffff), bf2f(rw.y >> 16)}; }
;                             else r = *(const f32x4*)(rp + col);
;                             const f32x4 v = r + acc[ai][bj][m][n] * scale;
;                             if (OUTF) *(f32x4*)(out + (size_t)row * DM + col) = v;
;                             else { u32x2 w; w.x = cvt_pk_bf16(v[0], v[1]); w.y = cvt_pk_bf16(v[2], v[3]); *(u32x2*)(outb + (size_t)row * DM + col) = w;
;                                 s += (v[0] * v[0] + v[1] * v[1]) + (v[2] * v[2] + v[3] * v[3]); } }
	v_and_b32_e32 v162, 0xffff0000, v144
	v_lshlrev_b32_e32 v144, 16, v144
	v_and_b32_e32 v163, 0xffff0000, v145
	v_lshlrev_b32_e32 v145, 16, v145
	v_add_f32_e32 v108, v108, v144
	v_add_f32_e32 v109, v109, v162
	v_add_f32_e32 v110, v110, v145
	v_add_f32_e32 v111, v111, v163
	v_mul_f32_e32 v144, v109, v109
	v_mul_f32_e32 v145, v111, v111
	v_fmac_f32_e32 v144, v108, v108
	v_fmac_f32_e32 v145, v110, v110
	v_add_f32_e32 v144, v144, v145
	v_mov_b32_e32 v172, v144
	v_cvt_pk_bf16_f32 v108, v108, v109
	v_cvt_pk_bf16_f32 v109, v110, v111
	v_and_b32_e32 v162, 0xffff0000, v146
	v_lshlrev_b32_e32 v146, 16, v146
	v_and_b32_e32 v163, 0xffff0000, v147
	v_lshlrev_b32_e32 v147, 16, v147
	v_add_f32_e32 v104, v104, v146
	v_add_f32_e32 v105, v105, v162
	v_add_f32_e32 v106, v106, v147
	v_add_f32_e32 v107, v107, v163
	v_mul_f32_e32 v146, v105, v105
	v_mul_f32_e32 v147, v107, v107
	v_fmac_f32_e32 v146, v104, v104
	v_fmac_f32_e32 v147, v106, v106
	v_add_f32_e32 v146, v146, v147
	v_add_f32_e32 v172, v172, v146
	v_cvt_pk_bf16_f32 v104, v104, v105
	v_cvt_pk_bf16_f32 v105, v106, v107
	v_and_b32_e32 v162, 0xffff0000, v148
	v_lshlrev_b32_e32 v148, 16, v148
	v_and_b32_e32 v163, 0xffff0000, v149
	v_lshlrev_b32_e32 v149, 16, v149
	v_add_f32_e32 v100, v100, v148
	v_add_f32_e32 v101, v101, v162
	v_add_f32_e32 v102, v102, v149
	v_add_f32_e32 v103, v103, v163
	v_mul_f32_e32 v148, v101, v101
	v_mul_f32_e32 v149, v103, v103
	v_fmac_f32_e32 v148, v100, v100
	v_fmac_f32_e32 v149, v102, v102
	v_add_f32_e32 v148, v148, v149
	v_add_f32_e32 v172, v172, v148
	v_cvt_pk_bf16_f32 v100, v100, v101
	v_cvt_pk_bf16_f32 v101, v102, v103
	v_and_b32_e32 v162, 0xffff0000, v150
	v_lshlrev_b32_e32 v150, 16, v150
	v_and_b32_e32 v163, 0xffff0000, v151
	v_lshlrev_b32_e32 v151, 16, v151
	v_add_f32_e32 v96, v96, v150
	v_add_f32_e32 v97, v97, v162
	v_add_f32_e32 v98, v98, v151
	v_add_f32_e32 v99, v99, v163
	v_mul_f32_e32 v150, v97, v97
	v_mul_f32_e32 v151, v99, v99
	v_fmac_f32_e32 v150, v96, v96
	v_fmac_f32_e32 v151, v98, v98
	v_add_f32_e32 v150, v150, v151
	v_add_f32_e32 v172, v172, v150
	v_cvt_pk_bf16_f32 v96, v96, v97
	v_cvt_pk_bf16_f32 v97, v98, v99
	v_mov_b32_e32 v110, v172
	v_add_u32_e32 v161, 0x48000, v160
	global_store_dwordx2 v161, v[108:109], s[18:19]
	global_store_dwordx2 v161, v[104:105], s[18:19] offset:32
	global_store_dwordx2 v161, v[100:101], s[18:19] offset:256
	global_store_dwordx2 v161, v[96:97], s[18:19] offset:288
	s_waitcnt vmcnt(28)
	v_and_b32_e32 v162, 0xffff0000, v152
	v_lshlrev_b32_e32 v152, 16, v152
	v_and_b32_e32 v163, 0xffff0000, v153
	v_lshlrev_b32_e32 v153, 16, v153
	v_add_f32_e32 v92, v92, v152
	v_add_f32_e32 v93, v93, v162
	v_add_f32_e32 v94, v94, v153
	v_add_f32_e32 v95, v95, v163
	v_mul_f32_e32 v152, v93, v93
	v_mul_f32_e32 v153, v95, v95
	v_fmac_f32_e32 v152, v92, v92
	v_fmac_f32_e32 v153, v94, v94
	v_add_f32_e32 v152, v152, v153
	v_mov_b32_e32 v172, v152
	v_cvt_pk_bf16_f32 v92, v92, v93
	v_cvt_pk_bf16_f32 v93, v94, v95
	v_and_b32_e32 v162, 0xffff0000, v154
	v_lshlrev_b32_e32 v154, 16, v154
	v_and_b32_e32 v163, 0xffff0000, v155
	v_lshlrev_b32_e32 v155, 16, v155
	v_add_f32_e32 v88, v88, v154
	v_add_f32_e32 v89, v89, v162
	v_add_f32_e32 v90, v90, v155
	v_add_f32_e32 v91, v91, v163
	v_mul_f32_e32 v154, v89, v89
	v_mul_f32_e32 v155, v91, v91
	v_fmac_f32_e32 v154, v88, v88
	v_fmac_f32_e32 v155, v90, v90
	v_add_f32_e32 v154, v154, v155
	v_add_f32_e32 v172, v172, v154
	v_cvt_pk_bf16_f32 v88, v88, v89
	v_cvt_pk_bf16_f32 v89, v90, v91
	v_and_b32_e32 v162, 0xffff0000, v156
	v_lshlrev_b32_e32 v156, 16, v156
	v_and_b32_e32 v163, 0xffff0000, v157
	v_lshlrev_b32_e32 v157, 16, v157
	v_add_f32_e32 v84, v84, v156
	v_add_f32_e32 v85, v85, v162
	v_add_f32_e32 v86, v86, v157
	v_add_f32_e32 v87, v87, v163
	v_mul_f32_e32 v156, v85, v85
	v_mul_f32_e32 v157, v87, v87
	v_fmac_f32_e32 v156, v84, v84
	v_fmac_f32_e32 v157, v86, v86
	v_add_f32_e32 v156, v156, v157
	v_add_f32_e32 v172, v172, v156
	v_cvt_pk_bf16_f32 v84, v84, v85
	v_cvt_pk_bf16_f32 v85, v86, v87
	v_and_b32_e32 v162, 0xffff0000, v158
	v_lshlrev_b32_e32 v158, 16, v158
	v_and_b32_e32 v163, 0xffff0000, v159
	v_lshlrev_b32_e32 v159, 16, v159
	v_add_f32_e32 v80, v80, v158
	v_add_f32_e32 v81, v81, v162
	v_add_f32_e32 v82, v82, v159
	v_add_f32_e32 v83, v83, v163
	v_mul_f32_e32 v158, v81, v81
	v_mul_f32_e32 v159, v83, v83
	v_fmac_f32_e32 v158, v80, v80
	v_fmac_f32_e32 v159, v82, v82
	v_add_f32_e32 v158, v158, v159
	v_add_f32_e32 v172, v172, v158
	v_cvt_pk_bf16_f32 v80, v80, v81
	v_cvt_pk_bf16_f32 v81, v82, v83
	v_mov_b32_e32 v94, v172
	v_add_u32_e32 v161, 0x50000, v160
	global_store_dwordx2 v161, v[92:93], s[18:19]
	global_store_dwordx2 v161, v[88:89], s[18:19] offset:32
	global_store_dwordx2 v161, v[84:85], s[18:19] offset:256
	global_store_dwordx2 v161, v[80:81], s[18:19] offset:288
	s_waitcnt vmcnt(28)
; __device__ __forceinline__ unsigned cvt_pk_bf16(float lo, float hi) { unsigned r; asm volatile("v_cvt_pk_bf16_f32 %0, %1, %2" : "=v"(r) : "v"(lo), "v"(hi)); return r; }
;     __device__ __forceinline__ void operator()(const f32x4 (&acc)[2][2][4][2], const pg8::Unit& u, int wr, int wc, int fr, int fq) const {
;     ...
;                     for (int bj = 0; bj < 2; ++bj)
; #pragma unroll
;                         for (int n = 0; n < 2; ++n) { const int col = col0 + bj * 128 + n * 16; f32x4 r;
;                             if (RESB) { const u32x2 rw = *(const u32x2*)(resb + (size_t)row * DM + col); r = (f32x4){bf2f(rw.x & 0xffff), bf2f(rw.x >> 16), bf2f(rw.y & 0xffff), bf2f(rw.y >> 16)}; }
;                             else r = *(const f32x4*)(rp + col);
;                             const f32x4 v = r + acc[ai][bj][m][n] * scale;
;                             if (OUTF) *(f32x4*)(out + (size_t)row * DM + col) = v;
;                             else { u32x2 w; w.x = cvt_pk_bf16(v[0], v[1]); w.y = cvt_pk_bf16(v[2], v[3]); *(u32x2*)(outb + (size_t)row * DM + col) = w;
;                                 s += (v[0] * v[0] + v[1] * v[1]) + (v[2] * v[2] + v[3] * v[3]); } }
;                     if (!OUTF) { s += __shfl_xor(s, 16); s += __shfl_xor(s, 32); if (fq == 0) atomicAdd(ss + row, s); }
	v_and_b32_e32 v162, 0xffff0000, v176
	v_lshlrev_b32_e32 v176, 16, v176
	v_and_b32_e32 v163, 0xffff0000, v177
	v_lshlrev_b32_e32 v177, 16, v177
	v_add_f32_e32 v76, v76, v176
	v_add_f32_e32 v77, v77, v162
	v_add_f32_e32 v78, v78, v177
	v_add_f32_e32 v79, v79, v163
	v_mul_f32_e32 v176, v77, v77
	v_mul_f32_e32 v177, v79, v79
	v_fmac_f32_e32 v176, v76, v76
	v_fmac_f32_e32 v177, v78, v78
	v_add_f32_e32 v176, v176, v177
	v_mov_b32_e32 v172, v176
	v_cvt_pk_bf16_f32 v76, v76, v77
	v_cvt_pk_bf16_f32 v77, v78, v79
	v_and_b32_e32 v162, 0xffff0000, v178
	v_lshlrev_b32_e32 v178, 16, v178
	v_and_b32_e32 v163, 0xffff0000, v179
	v_lshlrev_b32_e32 v179, 16, v179
	v_add_f32_e32 v72, v72, v178
	v_add_f32_e32 v73, v73, v162
	v_add_f32_e32 v74, v74, v179
	v_add_f32_e32 v75, v75, v163
	v_mul_f32_e32 v178, v73, v73
	v_mul_f32_e32 v179, v75, v75
	v_fmac_f32_e32 v178, v72, v72
	v_fmac_f32_e32 v179, v74, v74
	v_add_f32_e32 v178, v178, v179
	v_add_f32_e32 v172, v172, v178
	v_cvt_pk_bf16_f32 v72, v72, v73
	v_cvt_pk_bf16_f32 v73, v74, v75
	v_and_b32_e32 v162, 0xffff0000, v180
	v_lshlrev_b32_e32 v180, 16, v180
	v_and_b32_e32 v163, 0xffff0000, v181
	v_lshlrev_b32_e32 v181, 16, v181
	v_add_f32_e32 v68, v68, v180
	v_add_f32_e32 v69, v69, v162
	v_add_f32_e32 v70, v70, v181
	v_add_f32_e32 v71, v71, v163
	v_mul_f32_e32 v180, v69, v69
	v_mul_f32_e32 v181, v71, v71
	v_fmac_f32_e32 v180, v68, v68
	v_fmac_f32_e32 v181, v70, v70
	v_add_f32_e32 v180, v180, v181
	v_add_f32_e32 v172, v172, v180
	v_cvt_pk_bf16_f32 v68, v68, v69
	v_cvt_pk_bf16_f32 v69, v70, v71
	v_and_b32_e32 v162, 0xffff0000, v182
	v_lshlrev_b32_e32 v182, 16, v182
	v_and_b32_e32 v163, 0xffff0000, v183
	v_lshlrev_b32_e32 v183, 16, v183
	v_add_f32_e32 v56, v56, v182
	v_add_f32_e32 v57, v57, v162
	v_add_f32_e32 v58, v58, v183
	v_add_f32_e32 v59, v59, v163
	v_mul_f32_e32 v182, v57, v57
	v_mul_f32_e32 v183, v59, v59
	v_fmac_f32_e32 v182, v56, v56
	v_fmac_f32_e32 v183, v58, v58
	v_add_f32_e32 v182, v182, v183
	v_add_f32_e32 v172, v172, v182
	v_cvt_pk_bf16_f32 v56, v56, v57
	v_cvt_pk_bf16_f32 v57, v58, v59
	v_mov_b32_e32 v78, v172
	v_add_u32_e32 v161, 0x58000, v160
	global_store_dwordx2 v161, v[76:77], s[18:19]
	global_store_dwordx2 v161, v[72:73], s[18:19] offset:32
	global_store_dwordx2 v161, v[68:69], s[18:19] offset:256
	global_store_dwordx2 v161, v[56:57], s[18:19] offset:288
	v_xor_b32_e32 v173, 16, v170
	v_lshlrev_b32_e32 v173, 2, v173
	ds_bpermute_b32 v67, v173, v66
	ds_bpermute_b32 v51, v173, v50
	ds_bpermute_b32 v35, v173, v34
	ds_bpermute_b32 v19, v173, v18
	ds_bpermute_b32 v127, v173, v126
	ds_bpermute_b32 v111, v173, v110
	ds_bpermute_b32 v95, v173, v94
	ds_bpermute_b32 v79, v173, v78
	s_waitcnt lgkmcnt(0)
	v_add_f32_e32 v66, v66, v67
	v_add_f32_e32 v50, v50, v51
	v_add_f32_e32 v34, v34, v35
	v_add_f32_e32 v18, v18, v19
	v_add_f32_e32 v126, v126, v127
	v_add_f32_e32 v110, v110, v111
	v_add_f32_e32 v94, v94, v95
	v_add_f32_e32 v78, v78, v79
	v_xor_b32_e32 v173, 32, v170
	v_lshlrev_b32_e32 v173, 2, v173
	ds_bpermute_b32 v67, v173, v66
	ds_bpermute_b32 v51, v173, v50
	ds_bpermute_b32 v35, v173, v34
	ds_bpermute_b32 v19, v173, v18
	ds_bpermute_b32 v127, v173, v126
	ds_bpermute_b32 v111, v173, v110
	ds_bpermute_b32 v95, v173, v94
	ds_bpermute_b32 v79, v173, v78
	s_waitcnt lgkmcnt(0)
	v_add_f32_e32 v66, v66, v67
	v_add_f32_e32 v50, v50, v51
	v_add_f32_e32 v34, v34, v35
	v_add_f32_e32 v18, v18, v19
	v_add_f32_e32 v126, v126, v127
	v_add_f32_e32 v110, v110, v111
	v_add_f32_e32 v94, v94, v95
	v_add_f32_e32 v78, v78, v79
	v_lshl_add_u32 v160, s46, 8, v164
	v_lshlrev_b32_e32 v160, 2, v160
	s_and_saveexec_b64 s[0:1], s[8:9]
	global_atomic_add_f32 v160, v66, s[20:21]
	global_atomic_add_f32 v160, v50, s[20:21] offset:64
	global_atomic_add_f32 v160, v34, s[20:21] offset:128
	global_atomic_add_f32 v160, v18, s[20:21] offset:192
	global_atomic_add_f32 v160, v126, s[20:21] offset:512
	global_atomic_add_f32 v160, v110, s[20:21] offset:576
	global_atomic_add_f32 v160, v94, s[20:21] offset:640
	global_atomic_add_f32 v160, v78, s[20:21] offset:704
	s_or_b64 exec, exec, s[0:1]
	s_branch .Lp7e_done

; #define PG8_BAR __builtin_amdgcn_s_barrier()
; template <class Epi, class Sched, bool ALIGN_EPI = false, bool SP2 = false, class Bg = BgNone>
; __device__ __forceinline__ void gemm_phase(PG8_LAS unsigned char* lds, const Gemm g, const Sched& S, const Epi& E, const int wave_sg, const Bg& bg = Bg()) {
;     ...
;         if (!has_next) break;
; #pragma unroll
;         for (int a = 0; a < 2; ++a)
; #pragma unroll
;             for (int b = 0; b < 2; ++b)
; #pragma unroll
;                 for (int m = 0; m < 4; ++m)
; #pragma unroll
;                     for (int n = 0; n < 2; ++n) acc[a][b][m][n] = (f32x4){0.f, 0.f, 0.f, 0.f};
;         cur = nxt; cA = nA; cB = nB; ++ui;
;         if constexpr (ALIGN_EPI) { if (wr == 1) PG8_BAR; }
.Lp7e_done:
	s_andn2_b64 vcc, exec, s[12:13]
	s_mov_b64 s[0:1], -1
	s_cbranch_vccnz .LBB0_1041
	s_andn2_b64 vcc, exec, s[14:15]
	s_cbranch_vccnz .LBB0_1040
	s_barrier
	s_branch .LBB0_1040
